# up-projection tiles: first K iteration peeled with C=0 MFMAs, the 128 accumulator zeroing moves per tile removed
# speedup vs baseline: 1.0037x; 1.0036x over previous
.LBB0_362:
	s_ashr_i32 s23, s22, 31
	s_lshl_b64 s[24:25], s[22:23], 19
	s_add_u32 s24, s80, s24
	s_addc_u32 s25, s81, s25
	s_and_b64 s[26:27], s[6:7], exec
	s_cselect_b32 s23, s25, s35
	s_cselect_b32 s39, s24, s34
	s_ashr_i32 s21, s20, 31
	s_lshl_b64 s[26:27], s[20:21], 19
	s_add_u32 s26, s45, s26
	s_addc_u32 s27, s46, s27
	s_and_b64 s[36:37], s[6:7], exec
	s_cselect_b32 s21, s27, s31
	s_cselect_b32 s40, s26, s30
	s_add_u32 s41, s30, 0x100
	s_addc_u32 s43, s31, 0
	s_add_u32 s30, s34, 0x40080
	s_addc_u32 s31, s35, 0
	s_mov_b32 s56, -2
	s_add_u32 s34, s30, 0xfffc0080
	s_addc_u32 s35, s31, -1
	s_add_i32 s57, 0, 0x10000
	s_cmp_eq_u32 s56, 12
	s_cselect_b32 s37, s23, s35
	s_cselect_b32 s36, s39, s34
	v_add_u32_e32 v146, s57, v155
	s_cselect_b32 s35, s21, s43
	s_cselect_b32 s34, s40, s41
	s_add_i32 s60, 0, 0x14000
	ds_read_b128 v[142:145], v146
	ds_read_b128 v[168:171], v146 offset:1024
	ds_read_b128 v[172:175], v146 offset:2048
	ds_read_b128 v[176:179], v146 offset:3072
	v_add_u32_e32 v146, s60, v155
	ds_read_b128 v[180:183], v146
	ds_read_b128 v[184:187], v146 offset:1024
	ds_read_b128 v[188:191], v146 offset:2048
	ds_read_b128 v[192:195], v146 offset:3072
	v_lshl_add_u64 v[146:147], s[30:31], 0, v[140:141]
	s_add_i32 m0, s48, 0xc000
	ds_read_b128 v[196:199], v157
	ds_read_b128 v[200:203], v157 offset:1024
	ds_read_b128 v[204:207], v157 offset:2048
	ds_read_b128 v[220:223], v157 offset:3072
	ds_read_b128 v[236:239], v157 offset:4096
	ds_read_b128 v[240:243], v157 offset:5120
	ds_read_b128 v[244:247], v157 offset:6144
	ds_read_b128 v[248:251], v157 offset:7168
	global_load_lds_dwordx4 v[146:147], off
	v_lshl_add_u64 v[146:147], s[30:31], 0, v[138:139]
	s_add_i32 m0, s48, 0xe000
	s_nop 0
	global_load_lds_dwordx4 v[146:147], off
	s_nop 0
	s_nop 0
	s_nop 0
	s_nop 0
	s_nop 0
	s_nop 0
	s_nop 0
	s_nop 0
	s_nop 0
	s_nop 0
	s_waitcnt vmcnt(8)
	s_waitcnt lgkmcnt(0)
	s_barrier
	s_waitcnt lgkmcnt(0)
	v_mfma_f32_16x16x32_bf16 v[126:129], v[142:145], v[196:199], 0
	v_mfma_f32_16x16x32_bf16 v[118:121], v[172:175], v[196:199], 0
	v_mfma_f32_16x16x32_bf16 v[110:113], v[142:145], v[204:207], 0
	v_mfma_f32_16x16x32_bf16 v[102:105], v[172:175], v[204:207], 0
	v_mfma_f32_16x16x32_bf16 v[94:97], v[142:145], v[236:239], 0
	v_mfma_f32_16x16x32_bf16 v[86:89], v[172:175], v[236:239], 0
	v_mfma_f32_16x16x32_bf16 v[78:81], v[142:145], v[244:247], 0
	v_mfma_f32_16x16x32_bf16 v[70:73], v[172:175], v[244:247], 0
	v_mfma_f32_16x16x32_bf16 v[126:129], v[168:171], v[200:203], v[126:129]
	v_mfma_f32_16x16x32_bf16 v[118:121], v[176:179], v[200:203], v[118:121]
	v_mfma_f32_16x16x32_bf16 v[110:113], v[168:171], v[220:223], v[110:113]
	v_mfma_f32_16x16x32_bf16 v[102:105], v[176:179], v[220:223], v[102:105]
	v_mfma_f32_16x16x32_bf16 v[94:97], v[168:171], v[240:243], v[94:97]
	v_mfma_f32_16x16x32_bf16 v[86:89], v[176:179], v[240:243], v[86:89]
	v_mfma_f32_16x16x32_bf16 v[78:81], v[168:171], v[248:251], v[78:81]
	v_mfma_f32_16x16x32_bf16 v[70:73], v[176:179], v[248:251], v[70:73]
	v_mfma_f32_16x16x32_bf16 v[122:125], v[180:183], v[196:199], 0
	v_mfma_f32_16x16x32_bf16 v[114:117], v[188:191], v[196:199], 0
	v_mfma_f32_16x16x32_bf16 v[106:109], v[180:183], v[204:207], 0
	v_mfma_f32_16x16x32_bf16 v[98:101], v[188:191], v[204:207], 0
	v_mfma_f32_16x16x32_bf16 v[90:93], v[180:183], v[236:239], 0
	v_mfma_f32_16x16x32_bf16 v[82:85], v[188:191], v[236:239], 0
	v_mfma_f32_16x16x32_bf16 v[74:77], v[180:183], v[244:247], 0
	v_mfma_f32_16x16x32_bf16 v[66:69], v[188:191], v[244:247], 0
	v_mfma_f32_16x16x32_bf16 v[122:125], v[184:187], v[200:203], v[122:125]
	v_mfma_f32_16x16x32_bf16 v[114:117], v[192:195], v[200:203], v[114:117]
	v_mfma_f32_16x16x32_bf16 v[106:109], v[184:187], v[220:223], v[106:109]
	v_mfma_f32_16x16x32_bf16 v[98:101], v[192:195], v[220:223], v[98:101]
	v_mfma_f32_16x16x32_bf16 v[90:93], v[184:187], v[240:243], v[90:93]
	v_mfma_f32_16x16x32_bf16 v[82:85], v[192:195], v[240:243], v[82:85]
	v_mfma_f32_16x16x32_bf16 v[74:77], v[184:187], v[248:251], v[74:77]
	v_mfma_f32_16x16x32_bf16 v[66:69], v[192:195], v[248:251], v[66:69]
	s_barrier
	s_add_i32 s57, s57, s44
	v_lshl_add_u64 v[146:147], s[34:35], 0, v[134:135]
	s_mov_b32 m0, s57
	ds_read_b128 v[196:199], v157 offset:16384
	ds_read_b128 v[200:203], v157 offset:17408
	ds_read_b128 v[204:207], v157 offset:18432
	ds_read_b128 v[220:223], v157 offset:19456
	ds_read_b128 v[236:239], v157 offset:20480
	ds_read_b128 v[240:243], v157 offset:21504
	ds_read_b128 v[244:247], v157 offset:22528
	ds_read_b128 v[248:251], v157 offset:23552
	global_load_lds_dwordx4 v[146:147], off
	s_add_i32 m0, s57, 0x2000
	s_add_u32 s58, s34, 0x40000
	v_lshl_add_u64 v[208:209], s[34:35], 0, v[130:131]
	s_addc_u32 s59, s35, 0
	s_add_i32 s57, s60, s44
	global_load_lds_dwordx4 v[208:209], off
	v_lshl_add_u64 v[224:225], s[58:59], 0, v[134:135]
	s_mov_b32 m0, s57
	v_lshl_add_u64 v[230:231], s[36:37], 0, v[132:133]
	global_load_lds_dwordx4 v[224:225], off
	v_lshl_add_u64 v[224:225], s[58:59], 0, v[130:131]
	s_add_i32 m0, s57, 0x2000
	s_nop 0
	global_load_lds_dwordx4 v[224:225], off
	v_lshl_add_u64 v[224:225], s[36:37], 0, v[136:137]
	s_mov_b32 m0, s48
	s_nop 0
	global_load_lds_dwordx4 v[224:225], off
	s_mov_b32 m0, s49
	s_nop 0
	global_load_lds_dwordx4 v[230:231], off
	s_nop 0
	s_nop 0
	s_nop 0
	s_waitcnt vmcnt(8)
	s_waitcnt lgkmcnt(0)
	s_barrier
	s_waitcnt lgkmcnt(0)
	v_mfma_f32_16x16x32_bf16 v[62:65], v[142:145], v[196:199], 0
	v_mfma_f32_16x16x32_bf16 v[54:57], v[172:175], v[196:199], 0
	v_mfma_f32_16x16x32_bf16 v[46:49], v[142:145], v[204:207], 0
	v_mfma_f32_16x16x32_bf16 v[38:41], v[172:175], v[204:207], 0
	v_mfma_f32_16x16x32_bf16 v[30:33], v[142:145], v[236:239], 0
	v_mfma_f32_16x16x32_bf16 v[22:25], v[172:175], v[236:239], 0
	v_mfma_f32_16x16x32_bf16 v[14:17], v[142:145], v[244:247], 0
	v_mfma_f32_16x16x32_bf16 v[6:9], v[172:175], v[244:247], 0
	v_mfma_f32_16x16x32_bf16 v[62:65], v[168:171], v[200:203], v[62:65]
	v_mfma_f32_16x16x32_bf16 v[54:57], v[176:179], v[200:203], v[54:57]
	v_mfma_f32_16x16x32_bf16 v[46:49], v[168:171], v[220:223], v[46:49]
	v_mfma_f32_16x16x32_bf16 v[38:41], v[176:179], v[220:223], v[38:41]
	v_mfma_f32_16x16x32_bf16 v[30:33], v[168:171], v[240:243], v[30:33]
	v_mfma_f32_16x16x32_bf16 v[22:25], v[176:179], v[240:243], v[22:25]
	v_mfma_f32_16x16x32_bf16 v[14:17], v[168:171], v[248:251], v[14:17]
	v_mfma_f32_16x16x32_bf16 v[6:9], v[176:179], v[248:251], v[6:9]
	v_mfma_f32_16x16x32_bf16 v[58:61], v[180:183], v[196:199], 0
	v_mfma_f32_16x16x32_bf16 v[50:53], v[188:191], v[196:199], 0
	v_mfma_f32_16x16x32_bf16 v[42:45], v[180:183], v[204:207], 0
	v_mfma_f32_16x16x32_bf16 v[34:37], v[188:191], v[204:207], 0
	v_mfma_f32_16x16x32_bf16 v[26:29], v[180:183], v[236:239], 0
	v_mfma_f32_16x16x32_bf16 v[18:21], v[188:191], v[236:239], 0
	v_mfma_f32_16x16x32_bf16 v[10:13], v[180:183], v[244:247], 0
	v_mfma_f32_16x16x32_bf16 v[2:5], v[188:191], v[244:247], 0
	v_mfma_f32_16x16x32_bf16 v[58:61], v[184:187], v[200:203], v[58:61]
	v_mfma_f32_16x16x32_bf16 v[50:53], v[192:195], v[200:203], v[50:53]
	v_mfma_f32_16x16x32_bf16 v[42:45], v[184:187], v[220:223], v[42:45]
	v_mfma_f32_16x16x32_bf16 v[34:37], v[192:195], v[220:223], v[34:37]
	v_mfma_f32_16x16x32_bf16 v[26:29], v[184:187], v[240:243], v[26:29]
	v_mfma_f32_16x16x32_bf16 v[18:21], v[192:195], v[240:243], v[18:21]
	v_mfma_f32_16x16x32_bf16 v[10:13], v[184:187], v[248:251], v[10:13]
	v_mfma_f32_16x16x32_bf16 v[2:5], v[192:195], v[248:251], v[2:5]
	s_barrier
	s_add_i32 s57, 0, 0x18000
	v_add_u32_e32 v164, s57, v155
	s_add_i32 s58, 0, 0x1c000
	ds_read_b128 v[142:145], v164
	ds_read_b128 v[168:171], v164 offset:1024
	ds_read_b128 v[172:175], v164 offset:2048
	ds_read_b128 v[176:179], v164 offset:3072
	v_add_u32_e32 v164, s58, v155
	ds_read_b128 v[180:183], v164
	ds_read_b128 v[184:187], v164 offset:1024
	ds_read_b128 v[188:191], v164 offset:2048
	ds_read_b128 v[192:195], v164 offset:3072
	s_add_u32 s36, s36, 0x40000
	s_addc_u32 s37, s37, 0
	s_mov_b32 m0, s50
	v_lshl_add_u64 v[252:253], s[36:37], 0, v[136:137]
	ds_read_b128 v[196:199], v157 offset:32768
	ds_read_b128 v[200:203], v157 offset:33792
	ds_read_b128 v[204:207], v157 offset:34816
	ds_read_b128 v[220:223], v157 offset:35840
	ds_read_b128 v[236:239], v157 offset:36864
	ds_read_b128 v[240:243], v157 offset:37888
	ds_read_b128 v[244:247], v157 offset:38912
	ds_read_b128 v[248:251], v157 offset:39936
	global_load_lds_dwordx4 v[252:253], off
	v_lshl_add_u64 v[252:253], s[36:37], 0, v[132:133]
	s_mov_b32 m0, s51
	s_nop 0
	global_load_lds_dwordx4 v[252:253], off
	s_nop 0
	s_nop 0
	s_nop 0
	s_nop 0
	s_nop 0
	s_nop 0
	s_nop 0
	s_waitcnt vmcnt(8)
	s_waitcnt lgkmcnt(0)
	s_barrier
	s_waitcnt lgkmcnt(0)
	v_mfma_f32_16x16x32_bf16 v[126:129], v[142:145], v[196:199], v[126:129]
	v_mfma_f32_16x16x32_bf16 v[118:121], v[172:175], v[196:199], v[118:121]
	v_mfma_f32_16x16x32_bf16 v[110:113], v[142:145], v[204:207], v[110:113]
	v_mfma_f32_16x16x32_bf16 v[102:105], v[172:175], v[204:207], v[102:105]
	v_mfma_f32_16x16x32_bf16 v[94:97], v[142:145], v[236:239], v[94:97]
	v_mfma_f32_16x16x32_bf16 v[86:89], v[172:175], v[236:239], v[86:89]
	v_mfma_f32_16x16x32_bf16 v[78:81], v[142:145], v[244:247], v[78:81]
	v_mfma_f32_16x16x32_bf16 v[70:73], v[172:175], v[244:247], v[70:73]
	v_mfma_f32_16x16x32_bf16 v[126:129], v[168:171], v[200:203], v[126:129]
	v_mfma_f32_16x16x32_bf16 v[118:121], v[176:179], v[200:203], v[118:121]
	v_mfma_f32_16x16x32_bf16 v[110:113], v[168:171], v[220:223], v[110:113]
	v_mfma_f32_16x16x32_bf16 v[102:105], v[176:179], v[220:223], v[102:105]
	v_mfma_f32_16x16x32_bf16 v[94:97], v[168:171], v[240:243], v[94:97]
	v_mfma_f32_16x16x32_bf16 v[86:89], v[176:179], v[240:243], v[86:89]
	v_mfma_f32_16x16x32_bf16 v[78:81], v[168:171], v[248:251], v[78:81]
	v_mfma_f32_16x16x32_bf16 v[70:73], v[176:179], v[248:251], v[70:73]
	v_mfma_f32_16x16x32_bf16 v[122:125], v[180:183], v[196:199], v[122:125]
	v_mfma_f32_16x16x32_bf16 v[114:117], v[188:191], v[196:199], v[114:117]
	v_mfma_f32_16x16x32_bf16 v[106:109], v[180:183], v[204:207], v[106:109]
	v_mfma_f32_16x16x32_bf16 v[98:101], v[188:191], v[204:207], v[98:101]
	v_mfma_f32_16x16x32_bf16 v[90:93], v[180:183], v[236:239], v[90:93]
	v_mfma_f32_16x16x32_bf16 v[82:85], v[188:191], v[236:239], v[82:85]
	v_mfma_f32_16x16x32_bf16 v[74:77], v[180:183], v[244:247], v[74:77]
	v_mfma_f32_16x16x32_bf16 v[66:69], v[188:191], v[244:247], v[66:69]
	v_mfma_f32_16x16x32_bf16 v[122:125], v[184:187], v[200:203], v[122:125]
	v_mfma_f32_16x16x32_bf16 v[114:117], v[192:195], v[200:203], v[114:117]
	v_mfma_f32_16x16x32_bf16 v[106:109], v[184:187], v[220:223], v[106:109]
	v_mfma_f32_16x16x32_bf16 v[98:101], v[192:195], v[220:223], v[98:101]
	v_mfma_f32_16x16x32_bf16 v[90:93], v[184:187], v[240:243], v[90:93]
	v_mfma_f32_16x16x32_bf16 v[82:85], v[192:195], v[240:243], v[82:85]
	v_mfma_f32_16x16x32_bf16 v[74:77], v[184:187], v[248:251], v[74:77]
	v_mfma_f32_16x16x32_bf16 v[66:69], v[192:195], v[248:251], v[66:69]
	s_barrier
	s_add_i32 s36, s57, s44
	v_lshl_add_u64 v[146:147], v[146:147], 0, s[96:97]
	s_mov_b32 m0, s36
	ds_read_b128 v[196:199], v157 offset:49152
	ds_read_b128 v[200:203], v157 offset:50176
	ds_read_b128 v[204:207], v157 offset:51200
	ds_read_b128 v[220:223], v157 offset:52224
	ds_read_b128 v[236:239], v157 offset:53248
	ds_read_b128 v[240:243], v157 offset:54272
	ds_read_b128 v[244:247], v157 offset:55296
	ds_read_b128 v[248:251], v157 offset:56320
	global_load_lds_dwordx4 v[146:147], off
	s_add_i32 m0, s36, 0x2000
	s_add_u32 s34, s34, 0x40080
	v_lshl_add_u64 v[146:147], v[208:209], 0, s[96:97]
	s_addc_u32 s35, s35, 0
	s_add_i32 s36, s58, s44
	global_load_lds_dwordx4 v[146:147], off
	v_lshl_add_u64 v[146:147], s[34:35], 0, v[134:135]
	s_mov_b32 m0, s36
	s_nop 0
	global_load_lds_dwordx4 v[146:147], off
	v_lshl_add_u64 v[146:147], s[34:35], 0, v[130:131]
	s_add_i32 m0, s36, 0x2000
	s_nop 0
	global_load_lds_dwordx4 v[146:147], off
	v_lshl_add_u64 v[146:147], v[224:225], 0, s[96:97]
	s_mov_b32 m0, s52
	s_nop 0
	global_load_lds_dwordx4 v[146:147], off
	v_lshl_add_u64 v[146:147], v[230:231], 0, s[96:97]
	s_mov_b32 m0, s53
	s_nop 0
	global_load_lds_dwordx4 v[146:147], off
	s_nop 0
	s_nop 0
	s_waitcnt vmcnt(8)
	s_waitcnt lgkmcnt(0)
	s_barrier
	s_waitcnt lgkmcnt(0)
	v_mfma_f32_16x16x32_bf16 v[62:65], v[142:145], v[196:199], v[62:65]
	v_mfma_f32_16x16x32_bf16 v[54:57], v[172:175], v[196:199], v[54:57]
	v_mfma_f32_16x16x32_bf16 v[46:49], v[142:145], v[204:207], v[46:49]
	v_mfma_f32_16x16x32_bf16 v[38:41], v[172:175], v[204:207], v[38:41]
	v_mfma_f32_16x16x32_bf16 v[30:33], v[142:145], v[236:239], v[30:33]
	v_mfma_f32_16x16x32_bf16 v[22:25], v[172:175], v[236:239], v[22:25]
	v_mfma_f32_16x16x32_bf16 v[14:17], v[142:145], v[244:247], v[14:17]
	v_mfma_f32_16x16x32_bf16 v[6:9], v[172:175], v[244:247], v[6:9]
	v_mfma_f32_16x16x32_bf16 v[62:65], v[168:171], v[200:203], v[62:65]
	v_mfma_f32_16x16x32_bf16 v[54:57], v[176:179], v[200:203], v[54:57]
	v_mfma_f32_16x16x32_bf16 v[46:49], v[168:171], v[220:223], v[46:49]
	v_mfma_f32_16x16x32_bf16 v[38:41], v[176:179], v[220:223], v[38:41]
	v_mfma_f32_16x16x32_bf16 v[30:33], v[168:171], v[240:243], v[30:33]
	v_mfma_f32_16x16x32_bf16 v[22:25], v[176:179], v[240:243], v[22:25]
	v_mfma_f32_16x16x32_bf16 v[14:17], v[168:171], v[248:251], v[14:17]
	v_mfma_f32_16x16x32_bf16 v[6:9], v[176:179], v[248:251], v[6:9]
	v_mfma_f32_16x16x32_bf16 v[58:61], v[180:183], v[196:199], v[58:61]
	v_mfma_f32_16x16x32_bf16 v[50:53], v[188:191], v[196:199], v[50:53]
	v_mfma_f32_16x16x32_bf16 v[42:45], v[180:183], v[204:207], v[42:45]
	v_mfma_f32_16x16x32_bf16 v[34:37], v[188:191], v[204:207], v[34:37]
	v_mfma_f32_16x16x32_bf16 v[26:29], v[180:183], v[236:239], v[26:29]
	v_mfma_f32_16x16x32_bf16 v[18:21], v[188:191], v[236:239], v[18:21]
	v_mfma_f32_16x16x32_bf16 v[10:13], v[180:183], v[244:247], v[10:13]
	v_mfma_f32_16x16x32_bf16 v[2:5], v[188:191], v[244:247], v[2:5]
	v_mfma_f32_16x16x32_bf16 v[58:61], v[184:187], v[200:203], v[58:61]
	v_mfma_f32_16x16x32_bf16 v[50:53], v[192:195], v[200:203], v[50:53]
	v_mfma_f32_16x16x32_bf16 v[42:45], v[184:187], v[220:223], v[42:45]
	v_mfma_f32_16x16x32_bf16 v[34:37], v[192:195], v[220:223], v[34:37]
	v_mfma_f32_16x16x32_bf16 v[26:29], v[184:187], v[240:243], v[26:29]
	v_mfma_f32_16x16x32_bf16 v[18:21], v[192:195], v[240:243], v[18:21]
	v_mfma_f32_16x16x32_bf16 v[10:13], v[184:187], v[248:251], v[10:13]
	v_mfma_f32_16x16x32_bf16 v[2:5], v[192:195], v[248:251], v[2:5]
	s_barrier
	s_add_i32 s56, s56, 2
	s_add_u32 s41, s41, 0x100
	s_addc_u32 s43, s43, 0
	s_add_u32 s30, s30, 0x100
	s_addc_u32 s31, s31, 0
	s_cmp_gt_u32 s56, 13
.LBB0_363:
	s_add_u32 s34, s30, 0xfffc0080
	s_addc_u32 s35, s31, -1
	s_add_i32 s57, 0, 0x10000
	s_cmp_eq_u32 s56, 12
	s_cselect_b32 s37, s23, s35
	s_cselect_b32 s36, s39, s34
	v_add_u32_e32 v146, s57, v155
	s_cselect_b32 s35, s21, s43
	s_cselect_b32 s34, s40, s41
	s_add_i32 s60, 0, 0x14000
	ds_read_b128 v[142:145], v146
	ds_read_b128 v[168:171], v146 offset:1024
	ds_read_b128 v[172:175], v146 offset:2048
	ds_read_b128 v[176:179], v146 offset:3072
	v_add_u32_e32 v146, s60, v155
	ds_read_b128 v[180:183], v146
	ds_read_b128 v[184:187], v146 offset:1024
	ds_read_b128 v[188:191], v146 offset:2048
	ds_read_b128 v[192:195], v146 offset:3072
	v_lshl_add_u64 v[146:147], s[30:31], 0, v[140:141]
	s_add_i32 m0, s48, 0xc000
	ds_read_b128 v[196:199], v157
	ds_read_b128 v[200:203], v157 offset:1024
	ds_read_b128 v[204:207], v157 offset:2048
	ds_read_b128 v[220:223], v157 offset:3072
	ds_read_b128 v[236:239], v157 offset:4096
	ds_read_b128 v[240:243], v157 offset:5120
	ds_read_b128 v[244:247], v157 offset:6144
	ds_read_b128 v[248:251], v157 offset:7168
	global_load_lds_dwordx4 v[146:147], off
	v_lshl_add_u64 v[146:147], s[30:31], 0, v[138:139]
	s_add_i32 m0, s48, 0xe000
	s_nop 0
	global_load_lds_dwordx4 v[146:147], off
	s_nop 0
	s_nop 0
	s_nop 0
	s_nop 0
	s_nop 0
	s_nop 0
	s_nop 0
	s_nop 0
	s_nop 0
	s_nop 0
	s_nop 0
	s_nop 0
	s_nop 0
	s_nop 0
	s_nop 0
	s_nop 0
	s_nop 0
	s_nop 0
	s_nop 0
	s_nop 0
	s_nop 0
	s_nop 0
	s_nop 0
	s_nop 0
	s_waitcnt vmcnt(8)
	s_waitcnt lgkmcnt(0)
	s_barrier
	s_waitcnt lgkmcnt(0)
	v_mfma_f32_16x16x32_bf16 v[126:129], v[142:145], v[196:199], v[126:129]
	v_mfma_f32_16x16x32_bf16 v[118:121], v[172:175], v[196:199], v[118:121]
	v_mfma_f32_16x16x32_bf16 v[110:113], v[142:145], v[204:207], v[110:113]
	v_mfma_f32_16x16x32_bf16 v[102:105], v[172:175], v[204:207], v[102:105]
	v_mfma_f32_16x16x32_bf16 v[94:97], v[142:145], v[236:239], v[94:97]
	v_mfma_f32_16x16x32_bf16 v[86:89], v[172:175], v[236:239], v[86:89]
	v_mfma_f32_16x16x32_bf16 v[78:81], v[142:145], v[244:247], v[78:81]
	v_mfma_f32_16x16x32_bf16 v[70:73], v[172:175], v[244:247], v[70:73]
	v_mfma_f32_16x16x32_bf16 v[126:129], v[168:171], v[200:203], v[126:129]
	v_mfma_f32_16x16x32_bf16 v[118:121], v[176:179], v[200:203], v[118:121]
	v_mfma_f32_16x16x32_bf16 v[110:113], v[168:171], v[220:223], v[110:113]
	v_mfma_f32_16x16x32_bf16 v[102:105], v[176:179], v[220:223], v[102:105]
	v_mfma_f32_16x16x32_bf16 v[94:97], v[168:171], v[240:243], v[94:97]
	v_mfma_f32_16x16x32_bf16 v[86:89], v[176:179], v[240:243], v[86:89]
	v_mfma_f32_16x16x32_bf16 v[78:81], v[168:171], v[248:251], v[78:81]
	v_mfma_f32_16x16x32_bf16 v[70:73], v[176:179], v[248:251], v[70:73]
	v_mfma_f32_16x16x32_bf16 v[122:125], v[180:183], v[196:199], v[122:125]
	v_mfma_f32_16x16x32_bf16 v[114:117], v[188:191], v[196:199], v[114:117]
	v_mfma_f32_16x16x32_bf16 v[106:109], v[180:183], v[204:207], v[106:109]
	v_mfma_f32_16x16x32_bf16 v[98:101], v[188:191], v[204:207], v[98:101]
	v_mfma_f32_16x16x32_bf16 v[90:93], v[180:183], v[236:239], v[90:93]
	v_mfma_f32_16x16x32_bf16 v[82:85], v[188:191], v[236:239], v[82:85]
	v_mfma_f32_16x16x32_bf16 v[74:77], v[180:183], v[244:247], v[74:77]
	v_mfma_f32_16x16x32_bf16 v[66:69], v[188:191], v[244:247], v[66:69]
	v_mfma_f32_16x16x32_bf16 v[122:125], v[184:187], v[200:203], v[122:125]
	v_mfma_f32_16x16x32_bf16 v[114:117], v[192:195], v[200:203], v[114:117]
	v_mfma_f32_16x16x32_bf16 v[106:109], v[184:187], v[220:223], v[106:109]
	v_mfma_f32_16x16x32_bf16 v[98:101], v[192:195], v[220:223], v[98:101]
	v_mfma_f32_16x16x32_bf16 v[90:93], v[184:187], v[240:243], v[90:93]
	v_mfma_f32_16x16x32_bf16 v[82:85], v[192:195], v[240:243], v[82:85]
	v_mfma_f32_16x16x32_bf16 v[74:77], v[184:187], v[248:251], v[74:77]
	v_mfma_f32_16x16x32_bf16 v[66:69], v[192:195], v[248:251], v[66:69]
	s_barrier
	s_add_i32 s57, s57, s44
	v_lshl_add_u64 v[146:147], s[34:35], 0, v[134:135]
	s_mov_b32 m0, s57
	ds_read_b128 v[196:199], v157 offset:16384
	ds_read_b128 v[200:203], v157 offset:17408
	ds_read_b128 v[204:207], v157 offset:18432
	ds_read_b128 v[220:223], v157 offset:19456
	ds_read_b128 v[236:239], v157 offset:20480
	ds_read_b128 v[240:243], v157 offset:21504
	ds_read_b128 v[244:247], v157 offset:22528
	ds_read_b128 v[248:251], v157 offset:23552
	global_load_lds_dwordx4 v[146:147], off
	s_add_i32 m0, s57, 0x2000
	s_add_u32 s58, s34, 0x40000
	v_lshl_add_u64 v[208:209], s[34:35], 0, v[130:131]
	s_addc_u32 s59, s35, 0
	s_add_i32 s57, s60, s44
	global_load_lds_dwordx4 v[208:209], off
	v_lshl_add_u64 v[224:225], s[58:59], 0, v[134:135]
	s_mov_b32 m0, s57
	v_lshl_add_u64 v[230:231], s[36:37], 0, v[132:133]
	global_load_lds_dwordx4 v[224:225], off
	v_lshl_add_u64 v[224:225], s[58:59], 0, v[130:131]
	s_add_i32 m0, s57, 0x2000
	s_nop 0
	global_load_lds_dwordx4 v[224:225], off
	v_lshl_add_u64 v[224:225], s[36:37], 0, v[136:137]
	s_mov_b32 m0, s48
	s_nop 0
	global_load_lds_dwordx4 v[224:225], off
	s_mov_b32 m0, s49
	s_nop 0
	global_load_lds_dwordx4 v[230:231], off
	s_nop 0
	s_nop 0
	s_nop 0
	s_waitcnt vmcnt(8)
	s_waitcnt lgkmcnt(0)
	s_barrier
	s_waitcnt lgkmcnt(0)
	v_mfma_f32_16x16x32_bf16 v[62:65], v[142:145], v[196:199], v[62:65]
	v_mfma_f32_16x16x32_bf16 v[54:57], v[172:175], v[196:199], v[54:57]
	v_mfma_f32_16x16x32_bf16 v[46:49], v[142:145], v[204:207], v[46:49]
	v_mfma_f32_16x16x32_bf16 v[38:41], v[172:175], v[204:207], v[38:41]
	v_mfma_f32_16x16x32_bf16 v[30:33], v[142:145], v[236:239], v[30:33]
	v_mfma_f32_16x16x32_bf16 v[22:25], v[172:175], v[236:239], v[22:25]
	v_mfma_f32_16x16x32_bf16 v[14:17], v[142:145], v[244:247], v[14:17]
	v_mfma_f32_16x16x32_bf16 v[6:9], v[172:175], v[244:247], v[6:9]
	v_mfma_f32_16x16x32_bf16 v[62:65], v[168:171], v[200:203], v[62:65]
	v_mfma_f32_16x16x32_bf16 v[54:57], v[176:179], v[200:203], v[54:57]
	v_mfma_f32_16x16x32_bf16 v[46:49], v[168:171], v[220:223], v[46:49]
	v_mfma_f32_16x16x32_bf16 v[38:41], v[176:179], v[220:223], v[38:41]
	v_mfma_f32_16x16x32_bf16 v[30:33], v[168:171], v[240:243], v[30:33]
	v_mfma_f32_16x16x32_bf16 v[22:25], v[176:179], v[240:243], v[22:25]
	v_mfma_f32_16x16x32_bf16 v[14:17], v[168:171], v[248:251], v[14:17]
	v_mfma_f32_16x16x32_bf16 v[6:9], v[176:179], v[248:251], v[6:9]
	v_mfma_f32_16x16x32_bf16 v[58:61], v[180:183], v[196:199], v[58:61]
	v_mfma_f32_16x16x32_bf16 v[50:53], v[188:191], v[196:199], v[50:53]
	v_mfma_f32_16x16x32_bf16 v[42:45], v[180:183], v[204:207], v[42:45]
	v_mfma_f32_16x16x32_bf16 v[34:37], v[188:191], v[204:207], v[34:37]
	v_mfma_f32_16x16x32_bf16 v[26:29], v[180:183], v[236:239], v[26:29]
	v_mfma_f32_16x16x32_bf16 v[18:21], v[188:191], v[236:239], v[18:21]
	v_mfma_f32_16x16x32_bf16 v[10:13], v[180:183], v[244:247], v[10:13]
	v_mfma_f32_16x16x32_bf16 v[2:5], v[188:191], v[244:247], v[2:5]
	v_mfma_f32_16x16x32_bf16 v[58:61], v[184:187], v[200:203], v[58:61]
	v_mfma_f32_16x16x32_bf16 v[50:53], v[192:195], v[200:203], v[50:53]
	v_mfma_f32_16x16x32_bf16 v[42:45], v[184:187], v[220:223], v[42:45]
	v_mfma_f32_16x16x32_bf16 v[34:37], v[192:195], v[220:223], v[34:37]
	v_mfma_f32_16x16x32_bf16 v[26:29], v[184:187], v[240:243], v[26:29]
	v_mfma_f32_16x16x32_bf16 v[18:21], v[192:195], v[240:243], v[18:21]
	v_mfma_f32_16x16x32_bf16 v[10:13], v[184:187], v[248:251], v[10:13]
	v_mfma_f32_16x16x32_bf16 v[2:5], v[192:195], v[248:251], v[2:5]
	s_barrier
	s_add_i32 s57, 0, 0x18000
	v_add_u32_e32 v164, s57, v155
	s_add_i32 s58, 0, 0x1c000
	ds_read_b128 v[142:145], v164
	ds_read_b128 v[168:171], v164 offset:1024
	ds_read_b128 v[172:175], v164 offset:2048
	ds_read_b128 v[176:179], v164 offset:3072
	v_add_u32_e32 v164, s58, v155
	ds_read_b128 v[180:183], v164
	ds_read_b128 v[184:187], v164 offset:1024
	ds_read_b128 v[188:191], v164 offset:2048
	ds_read_b128 v[192:195], v164 offset:3072
	s_add_u32 s36, s36, 0x40000
	s_addc_u32 s37, s37, 0
	s_mov_b32 m0, s50
	v_lshl_add_u64 v[252:253], s[36:37], 0, v[136:137]
	ds_read_b128 v[196:199], v157 offset:32768
	ds_read_b128 v[200:203], v157 offset:33792
	ds_read_b128 v[204:207], v157 offset:34816
	ds_read_b128 v[220:223], v157 offset:35840
	ds_read_b128 v[236:239], v157 offset:36864
	ds_read_b128 v[240:243], v157 offset:37888
	ds_read_b128 v[244:247], v157 offset:38912
	ds_read_b128 v[248:251], v157 offset:39936
	global_load_lds_dwordx4 v[252:253], off
	v_lshl_add_u64 v[252:253], s[36:37], 0, v[132:133]
	s_mov_b32 m0, s51
	s_nop 0
	global_load_lds_dwordx4 v[252:253], off
	s_nop 0
	s_nop 0
	s_nop 0
	s_nop 0
	s_nop 0
	s_nop 0
	s_nop 0
	s_waitcnt vmcnt(8)
	s_waitcnt lgkmcnt(0)
	s_barrier
	s_waitcnt lgkmcnt(0)
	v_mfma_f32_16x16x32_bf16 v[126:129], v[142:145], v[196:199], v[126:129]
	v_mfma_f32_16x16x32_bf16 v[118:121], v[172:175], v[196:199], v[118:121]
	v_mfma_f32_16x16x32_bf16 v[110:113], v[142:145], v[204:207], v[110:113]
	v_mfma_f32_16x16x32_bf16 v[102:105], v[172:175], v[204:207], v[102:105]
	v_mfma_f32_16x16x32_bf16 v[94:97], v[142:145], v[236:239], v[94:97]
	v_mfma_f32_16x16x32_bf16 v[86:89], v[172:175], v[236:239], v[86:89]
	v_mfma_f32_16x16x32_bf16 v[78:81], v[142:145], v[244:247], v[78:81]
	v_mfma_f32_16x16x32_bf16 v[70:73], v[172:175], v[244:247], v[70:73]
	v_mfma_f32_16x16x32_bf16 v[126:129], v[168:171], v[200:203], v[126:129]
	v_mfma_f32_16x16x32_bf16 v[118:121], v[176:179], v[200:203], v[118:121]
	v_mfma_f32_16x16x32_bf16 v[110:113], v[168:171], v[220:223], v[110:113]
	v_mfma_f32_16x16x32_bf16 v[102:105], v[176:179], v[220:223], v[102:105]
	v_mfma_f32_16x16x32_bf16 v[94:97], v[168:171], v[240:243], v[94:97]
	v_mfma_f32_16x16x32_bf16 v[86:89], v[176:179], v[240:243], v[86:89]
	v_mfma_f32_16x16x32_bf16 v[78:81], v[168:171], v[248:251], v[78:81]
	v_mfma_f32_16x16x32_bf16 v[70:73], v[176:179], v[248:251], v[70:73]
	v_mfma_f32_16x16x32_bf16 v[122:125], v[180:183], v[196:199], v[122:125]
	v_mfma_f32_16x16x32_bf16 v[114:117], v[188:191], v[196:199], v[114:117]
	v_mfma_f32_16x16x32_bf16 v[106:109], v[180:183], v[204:207], v[106:109]
	v_mfma_f32_16x16x32_bf16 v[98:101], v[188:191], v[204:207], v[98:101]
	v_mfma_f32_16x16x32_bf16 v[90:93], v[180:183], v[236:239], v[90:93]
	v_mfma_f32_16x16x32_bf16 v[82:85], v[188:191], v[236:239], v[82:85]
	v_mfma_f32_16x16x32_bf16 v[74:77], v[180:183], v[244:247], v[74:77]
	v_mfma_f32_16x16x32_bf16 v[66:69], v[188:191], v[244:247], v[66:69]
	v_mfma_f32_16x16x32_bf16 v[122:125], v[184:187], v[200:203], v[122:125]
	v_mfma_f32_16x16x32_bf16 v[114:117], v[192:195], v[200:203], v[114:117]
	v_mfma_f32_16x16x32_bf16 v[106:109], v[184:187], v[220:223], v[106:109]
	v_mfma_f32_16x16x32_bf16 v[98:101], v[192:195], v[220:223], v[98:101]
	v_mfma_f32_16x16x32_bf16 v[90:93], v[184:187], v[240:243], v[90:93]
	v_mfma_f32_16x16x32_bf16 v[82:85], v[192:195], v[240:243], v[82:85]
	v_mfma_f32_16x16x32_bf16 v[74:77], v[184:187], v[248:251], v[74:77]
	v_mfma_f32_16x16x32_bf16 v[66:69], v[192:195], v[248:251], v[66:69]
	s_barrier
	s_add_i32 s36, s57, s44
	v_lshl_add_u64 v[146:147], v[146:147], 0, s[96:97]
	s_mov_b32 m0, s36
	ds_read_b128 v[196:199], v157 offset:49152
	ds_read_b128 v[200:203], v157 offset:50176
	ds_read_b128 v[204:207], v157 offset:51200
	ds_read_b128 v[220:223], v157 offset:52224
	ds_read_b128 v[236:239], v157 offset:53248
	ds_read_b128 v[240:243], v157 offset:54272
	ds_read_b128 v[244:247], v157 offset:55296
	ds_read_b128 v[248:251], v157 offset:56320
	global_load_lds_dwordx4 v[146:147], off
	s_add_i32 m0, s36, 0x2000
	s_add_u32 s34, s34, 0x40080
	v_lshl_add_u64 v[146:147], v[208:209], 0, s[96:97]
	s_addc_u32 s35, s35, 0
	s_add_i32 s36, s58, s44
	global_load_lds_dwordx4 v[146:147], off
	v_lshl_add_u64 v[146:147], s[34:35], 0, v[134:135]
	s_mov_b32 m0, s36
	s_nop 0
	global_load_lds_dwordx4 v[146:147], off
	v_lshl_add_u64 v[146:147], s[34:35], 0, v[130:131]
	s_add_i32 m0, s36, 0x2000
	s_nop 0
	global_load_lds_dwordx4 v[146:147], off
	v_lshl_add_u64 v[146:147], v[224:225], 0, s[96:97]
	s_mov_b32 m0, s52
	s_nop 0
	global_load_lds_dwordx4 v[146:147], off
	v_lshl_add_u64 v[146:147], v[230:231], 0, s[96:97]
	s_mov_b32 m0, s53
	s_nop 0
	global_load_lds_dwordx4 v[146:147], off
	s_nop 0
	s_nop 0
	s_waitcnt vmcnt(8)
	s_waitcnt lgkmcnt(0)
	s_barrier
	s_waitcnt lgkmcnt(0)
	v_mfma_f32_16x16x32_bf16 v[62:65], v[142:145], v[196:199], v[62:65]
	v_mfma_f32_16x16x32_bf16 v[54:57], v[172:175], v[196:199], v[54:57]
	v_mfma_f32_16x16x32_bf16 v[46:49], v[142:145], v[204:207], v[46:49]
	v_mfma_f32_16x16x32_bf16 v[38:41], v[172:175], v[204:207], v[38:41]
	v_mfma_f32_16x16x32_bf16 v[30:33], v[142:145], v[236:239], v[30:33]
	v_mfma_f32_16x16x32_bf16 v[22:25], v[172:175], v[236:239], v[22:25]
	v_mfma_f32_16x16x32_bf16 v[14:17], v[142:145], v[244:247], v[14:17]
	v_mfma_f32_16x16x32_bf16 v[6:9], v[172:175], v[244:247], v[6:9]
	v_mfma_f32_16x16x32_bf16 v[62:65], v[168:171], v[200:203], v[62:65]
	v_mfma_f32_16x16x32_bf16 v[54:57], v[176:179], v[200:203], v[54:57]
	v_mfma_f32_16x16x32_bf16 v[46:49], v[168:171], v[220:223], v[46:49]
	v_mfma_f32_16x16x32_bf16 v[38:41], v[176:179], v[220:223], v[38:41]
	v_mfma_f32_16x16x32_bf16 v[30:33], v[168:171], v[240:243], v[30:33]
	v_mfma_f32_16x16x32_bf16 v[22:25], v[176:179], v[240:243], v[22:25]
	v_mfma_f32_16x16x32_bf16 v[14:17], v[168:171], v[248:251], v[14:17]
	v_mfma_f32_16x16x32_bf16 v[6:9], v[176:179], v[248:251], v[6:9]
	v_mfma_f32_16x16x32_bf16 v[58:61], v[180:183], v[196:199], v[58:61]
	v_mfma_f32_16x16x32_bf16 v[50:53], v[188:191], v[196:199], v[50:53]
	v_mfma_f32_16x16x32_bf16 v[42:45], v[180:183], v[204:207], v[42:45]
	v_mfma_f32_16x16x32_bf16 v[34:37], v[188:191], v[204:207], v[34:37]
	v_mfma_f32_16x16x32_bf16 v[26:29], v[180:183], v[236:239], v[26:29]
	v_mfma_f32_16x16x32_bf16 v[18:21], v[188:191], v[236:239], v[18:21]
	v_mfma_f32_16x16x32_bf16 v[10:13], v[180:183], v[244:247], v[10:13]
	v_mfma_f32_16x16x32_bf16 v[2:5], v[188:191], v[244:247], v[2:5]
	v_mfma_f32_16x16x32_bf16 v[58:61], v[184:187], v[200:203], v[58:61]
	v_mfma_f32_16x16x32_bf16 v[50:53], v[192:195], v[200:203], v[50:53]
	v_mfma_f32_16x16x32_bf16 v[42:45], v[184:187], v[220:223], v[42:45]
	v_mfma_f32_16x16x32_bf16 v[34:37], v[192:195], v[220:223], v[34:37]
	v_mfma_f32_16x16x32_bf16 v[26:29], v[184:187], v[240:243], v[26:29]
	v_mfma_f32_16x16x32_bf16 v[18:21], v[192:195], v[240:243], v[18:21]
	v_mfma_f32_16x16x32_bf16 v[10:13], v[184:187], v[248:251], v[10:13]
	v_mfma_f32_16x16x32_bf16 v[2:5], v[192:195], v[248:251], v[2:5]
	s_barrier
	s_add_i32 s56, s56, 2
	s_add_u32 s41, s41, 0x100
	s_addc_u32 s43, s43, 0
	s_add_u32 s30, s30, 0x100
	s_addc_u32 s31, s31, 0
	s_cmp_gt_u32 s56, 13
	s_cbranch_scc0 .LBB0_363
	s_and_b64 vcc, exec, s[16:17]
	s_cbranch_vccz .LBB0_366
	s_barrier
